# attention loop VALU trim: packed max-subtract, packed row-sum tree, V loads via saddr, hoisted lane-swizzle calc
# speedup vs baseline: 1.0107x; 1.0031x over previous
.LBB0_264:
	s_waitcnt lgkmcnt(0)
	ds_read_b128 v[80:83], v215
	ds_read_b128 v[84:87], v215 offset:32
	ds_read_b128 v[88:91], v215 offset:64
	ds_read_b128 v[92:95], v215 offset:96
	s_cmp_lg_u32 s28, 7
	s_cselect_b64 s[4:5], -1, 0
	s_cmp_eq_u32 s28, 7
	s_waitcnt vmcnt(4)
	ds_write_b128 v245, v[96:99]
	ds_write_b128 v245, v[100:103] offset:1152
	ds_write_b128 v245, v[104:107] offset:2304
	ds_write_b128 v245, v[108:111] offset:3456
	ds_write_b128 v245, v[114:117] offset:4608
	ds_write_b128 v245, v[118:121] offset:5760
	ds_write_b128 v245, v[122:125] offset:6912
	ds_write_b128 v245, v[126:129] offset:8064
	s_cbranch_scc1 .LBB0_266
	s_add_i32 s40, s11, 64
	s_mul_i32 s40, s40, 0x1c00
	s_add_i32 s40, s40, 0x6000000
	s_add_u32 s40, s2, s40
	s_addc_u32 s41, s3, 0
	global_load_dwordx4 v[96:99], v213, s[40:41] offset:1024
	s_add_u32 s40, s40, 0xe000
	s_addc_u32 s41, s41, 0
	global_load_dwordx4 v[100:103], v213, s[40:41] offset:1024
	s_add_u32 s40, s40, 0xe000
	s_addc_u32 s41, s41, 0
	global_load_dwordx4 v[104:107], v213, s[40:41] offset:1024
	s_add_u32 s40, s40, 0xe000
	s_addc_u32 s41, s41, 0
	global_load_dwordx4 v[108:111], v213, s[40:41] offset:1024
	s_add_u32 s40, s40, 0xe000
	s_addc_u32 s41, s41, 0
	global_load_dwordx4 v[114:117], v213, s[40:41] offset:1024
	s_add_u32 s40, s40, 0xe000
	s_addc_u32 s41, s41, 0
	global_load_dwordx4 v[118:121], v213, s[40:41] offset:1024
	s_add_u32 s40, s40, 0xe000
	s_addc_u32 s41, s41, 0
	global_load_dwordx4 v[122:125], v213, s[40:41] offset:1024
	s_add_u32 s40, s40, 0xe000
	s_addc_u32 s41, s41, 0
	global_load_dwordx4 v[126:129], v213, s[40:41] offset:1024

.LBB0_270:
	v_max_f32_e32 v48, v32, v33
	v_max3_f32 v48, v48, v34, v35
	v_max3_f32 v48, v48, v36, v37
	v_max3_f32 v48, v48, v38, v39
	v_max3_f32 v48, v48, v40, v41
	v_max3_f32 v48, v48, v42, v43
	v_max3_f32 v48, v48, v44, v45
	v_max3_f32 v48, v48, v46, v47
	v_mov_b32_e32 v49, v48
	s_nop 1
	v_permlane32_swap_b32_e32 v49, v48
	v_max3_f32 v191, v233, v49, v48
	v_add_f32_e32 v48, 0x41000000, v233
	v_cmp_gt_f32_e32 vcc, v191, v48
	s_cbranch_vccnz .Latt_updA
	v_mov_b32_e32 v191, v233
	v_mov_b32_e32 v198, 1.0
	s_branch .LBB0_272

.LBB0_272:
	s_waitcnt lgkmcnt(0)
	v_mfma_f32_32x32x16_bf16 v[216:231], v[80:83], v[64:67], 0
	v_pk_add_f32 v[32:33], v[32:33], v[190:191] op_sel:[0,1] op_sel_hi:[1,1] neg_lo:[0,1] neg_hi:[0,1]
	v_pk_add_f32 v[34:35], v[34:35], v[190:191] op_sel:[0,1] op_sel_hi:[1,1] neg_lo:[0,1] neg_hi:[0,1]
	v_pk_add_f32 v[36:37], v[36:37], v[190:191] op_sel:[0,1] op_sel_hi:[1,1] neg_lo:[0,1] neg_hi:[0,1]
	v_pk_add_f32 v[38:39], v[38:39], v[190:191] op_sel:[0,1] op_sel_hi:[1,1] neg_lo:[0,1] neg_hi:[0,1]
	v_pk_add_f32 v[40:41], v[40:41], v[190:191] op_sel:[0,1] op_sel_hi:[1,1] neg_lo:[0,1] neg_hi:[0,1]
	v_pk_add_f32 v[42:43], v[42:43], v[190:191] op_sel:[0,1] op_sel_hi:[1,1] neg_lo:[0,1] neg_hi:[0,1]
	v_pk_add_f32 v[44:45], v[44:45], v[190:191] op_sel:[0,1] op_sel_hi:[1,1] neg_lo:[0,1] neg_hi:[0,1]
	v_pk_add_f32 v[46:47], v[46:47], v[190:191] op_sel:[0,1] op_sel_hi:[1,1] neg_lo:[0,1] neg_hi:[0,1]
	v_exp_f32_e32 v32, v32
	v_exp_f32_e32 v33, v33
	v_exp_f32_e32 v34, v34
	v_exp_f32_e32 v35, v35
	v_mfma_f32_32x32x16_bf16 v[216:231], v[84:87], v[68:71], v[216:231]
	v_exp_f32_e32 v36, v36
	v_exp_f32_e32 v37, v37
	v_exp_f32_e32 v38, v38
	v_exp_f32_e32 v39, v39
	v_exp_f32_e32 v40, v40
	v_exp_f32_e32 v41, v41
	v_exp_f32_e32 v42, v42
	v_exp_f32_e32 v43, v43
	v_mfma_f32_32x32x16_bf16 v[216:231], v[88:91], v[72:75], v[216:231]
	v_exp_f32_e32 v44, v44
	v_exp_f32_e32 v45, v45
	v_exp_f32_e32 v46, v46
	v_exp_f32_e32 v47, v47
	v_mfma_f32_32x32x16_bf16 v[216:231], v[92:95], v[76:79], v[216:231]
	v_pk_add_f32 v[200:201], v[32:33], v[34:35]
	v_pk_add_f32 v[202:203], v[36:37], v[38:39]
	v_pk_add_f32 v[204:205], v[40:41], v[42:43]
	v_pk_add_f32 v[206:207], v[44:45], v[46:47]
	v_cvt_pk_bf16_f32 v32, v32, v33
	v_cvt_pk_bf16_f32 v33, v34, v35
	v_cvt_pk_bf16_f32 v34, v36, v37
	v_cvt_pk_bf16_f32 v35, v38, v39
	v_pk_add_f32 v[200:201], v[200:201], v[202:203]
	v_pk_add_f32 v[204:205], v[204:205], v[206:207]
	v_cvt_pk_bf16_f32 v36, v40, v41
	v_cvt_pk_bf16_f32 v37, v42, v43
	v_mfma_f32_32x32x16_bf16 v[16:31], v[142:145], v[32:35], v[16:31]
	v_cvt_pk_bf16_f32 v38, v44, v45
	v_cvt_pk_bf16_f32 v39, v46, v47
	v_pk_add_f32 v[200:201], v[200:201], v[204:205]
	v_mfma_f32_32x32x16_bf16 v[0:15], v[130:133], v[32:35], v[0:15]
	v_nop
	v_add_f32_e32 v192, v200, v201
	v_fmac_f32_e32 v192, v251, v198
	v_mfma_f32_32x32x16_bf16 v[16:31], v[138:141], v[36:39], v[16:31]
	v_mfma_f32_32x32x16_bf16 v[0:15], v[134:137], v[36:39], v[0:15]

.LBB0_278:
	v_max_f32_e32 v48, v32, v33
	v_max3_f32 v48, v48, v34, v35
	v_max3_f32 v48, v48, v36, v37
	v_max3_f32 v48, v48, v38, v39
	v_max3_f32 v48, v48, v40, v41
	v_max3_f32 v48, v48, v42, v43
	v_max3_f32 v48, v48, v44, v45
	v_max3_f32 v48, v48, v46, v47
	v_mov_b32_e32 v49, v48
	s_nop 1
	v_permlane32_swap_b32_e32 v49, v48
	v_max3_f32 v233, v191, v49, v48
	v_add_f32_e32 v48, 0x41000000, v191
	v_cmp_gt_f32_e32 vcc, v233, v48
	s_cbranch_vccnz .Latt_updB
	v_mov_b32_e32 v233, v191
	v_mov_b32_e32 v48, 1.0
	s_branch .LBB0_280

.LBB0_280:
	v_pk_add_f32 v[32:33], v[32:33], v[232:233] op_sel:[0,1] op_sel_hi:[1,1] neg_lo:[0,1] neg_hi:[0,1]
	v_pk_add_f32 v[34:35], v[34:35], v[232:233] op_sel:[0,1] op_sel_hi:[1,1] neg_lo:[0,1] neg_hi:[0,1]
	v_pk_add_f32 v[36:37], v[36:37], v[232:233] op_sel:[0,1] op_sel_hi:[1,1] neg_lo:[0,1] neg_hi:[0,1]
	v_pk_add_f32 v[38:39], v[38:39], v[232:233] op_sel:[0,1] op_sel_hi:[1,1] neg_lo:[0,1] neg_hi:[0,1]
	v_pk_add_f32 v[40:41], v[40:41], v[232:233] op_sel:[0,1] op_sel_hi:[1,1] neg_lo:[0,1] neg_hi:[0,1]
	v_pk_add_f32 v[42:43], v[42:43], v[232:233] op_sel:[0,1] op_sel_hi:[1,1] neg_lo:[0,1] neg_hi:[0,1]
	v_pk_add_f32 v[44:45], v[44:45], v[232:233] op_sel:[0,1] op_sel_hi:[1,1] neg_lo:[0,1] neg_hi:[0,1]
	v_pk_add_f32 v[46:47], v[46:47], v[232:233] op_sel:[0,1] op_sel_hi:[1,1] neg_lo:[0,1] neg_hi:[0,1]
	v_exp_f32_e32 v32, v32
	v_exp_f32_e32 v33, v33
	v_exp_f32_e32 v34, v34
	v_exp_f32_e32 v35, v35
	v_exp_f32_e32 v36, v36
	v_exp_f32_e32 v37, v37
	v_exp_f32_e32 v38, v38
	v_exp_f32_e32 v39, v39
	v_exp_f32_e32 v40, v40
	v_exp_f32_e32 v41, v41
	v_exp_f32_e32 v42, v42
	v_exp_f32_e32 v43, v43
	v_pk_add_f32 v[200:201], v[32:33], v[34:35]
	v_pk_add_f32 v[202:203], v[36:37], v[38:39]
	v_cvt_pk_bf16_f32 v32, v32, v33
	v_cvt_pk_bf16_f32 v33, v34, v35
	v_cvt_pk_bf16_f32 v34, v36, v37
	v_cvt_pk_bf16_f32 v35, v38, v39
	v_exp_f32_e32 v44, v44
	v_exp_f32_e32 v45, v45
	v_exp_f32_e32 v46, v46
	v_exp_f32_e32 v47, v47
	v_pk_add_f32 v[200:201], v[200:201], v[202:203]
	s_waitcnt lgkmcnt(0)
	v_mfma_f32_32x32x16_bf16 v[16:31], v[142:145], v[32:35], v[16:31]
	v_pk_add_f32 v[204:205], v[40:41], v[42:43]
	v_mfma_f32_32x32x16_bf16 v[0:15], v[134:137], v[32:35], v[0:15]
	v_pk_add_f32 v[206:207], v[44:45], v[46:47]
	v_cvt_pk_bf16_f32 v36, v40, v41
	v_cvt_pk_bf16_f32 v37, v42, v43
	v_cvt_pk_bf16_f32 v38, v44, v45
	v_cvt_pk_bf16_f32 v39, v46, v47
	v_pk_add_f32 v[204:205], v[204:205], v[206:207]
	s_add_i32 s11, s11, 64
	v_subrev_u32_e32 v247, 64, v247
	v_mfma_f32_32x32x16_bf16 v[16:31], v[138:141], v[36:39], v[16:31]
	v_pk_add_f32 v[200:201], v[200:201], v[204:205]
	v_mfma_f32_32x32x16_bf16 v[0:15], v[130:133], v[36:39], v[0:15]
	v_nop
	v_add_f32_e32 v251, v200, v201
	v_fmac_f32_e32 v251, v192, v48
	s_cmp_gt_u32 s28, 7
	s_cbranch_scc1 .LBB0_282
	s_branch .LBB0_264

.LBB0_282:
	v_xor_b32_e32 v32, 32, v236
	v_add_u32_e32 v33, 64, v237
	v_cmp_lt_i32_e32 vcc, v32, v33
	v_cndmask_b32_e32 v32, v236, v32, vcc
	v_lshlrev_b32_e32 v189, 2, v32
	ds_bpermute_b32 v32, v189, v251
	s_waitcnt lgkmcnt(0)
	v_add_f32_e32 v32, v251, v32
	v_div_scale_f32 v33, s[0:1], v32, v32, 1.0
	v_rcp_f32_e32 v34, v33
	v_div_scale_f32 v35, vcc, 1.0, v32, 1.0
	v_fma_f32 v36, -v33, v34, 1.0
	v_fmac_f32_e32 v34, v36, v34
	v_mul_f32_e32 v36, v35, v34
	v_fma_f32 v37, -v33, v36, v35
	v_fmac_f32_e32 v36, v37, v34
	v_fma_f32 v33, -v33, v36, v35
	v_div_fmas_f32 v33, v33, v34, v36
	v_div_fixup_f32 v36, v33, v32, 1.0
	v_pk_mul_f32 v[34:35], v[16:17], v[36:37] op_sel_hi:[1,0]
	v_pk_mul_f32 v[32:33], v[18:19], v[36:37] op_sel_hi:[1,0]
	v_mul_f32_e32 v16, v35, v35
	v_fmac_f32_e32 v16, v34, v34
	v_fmac_f32_e32 v16, v32, v32
	v_pk_mul_f32 v[20:21], v[20:21], v[36:37] op_sel_hi:[1,0]
	v_fmac_f32_e32 v16, v33, v33
	v_fmac_f32_e32 v16, v20, v20
	v_pk_mul_f32 v[22:23], v[22:23], v[36:37] op_sel_hi:[1,0]
	v_fmac_f32_e32 v16, v21, v21
	v_fmac_f32_e32 v16, v22, v22
	v_pk_mul_f32 v[24:25], v[24:25], v[36:37] op_sel_hi:[1,0]
	v_fmac_f32_e32 v16, v23, v23
	v_fmac_f32_e32 v16, v24, v24
	v_pk_mul_f32 v[26:27], v[26:27], v[36:37] op_sel_hi:[1,0]
	v_fmac_f32_e32 v16, v25, v25
	v_fmac_f32_e32 v16, v26, v26
	v_pk_mul_f32 v[28:29], v[28:29], v[36:37] op_sel_hi:[1,0]
	v_fmac_f32_e32 v16, v27, v27
	v_fmac_f32_e32 v16, v28, v28
	v_pk_mul_f32 v[30:31], v[30:31], v[36:37] op_sel_hi:[1,0]
	v_fmac_f32_e32 v16, v29, v29
	v_fmac_f32_e32 v16, v30, v30
	v_fmac_f32_e32 v16, v31, v31
	v_pk_mul_f32 v[0:1], v[0:1], v[36:37] op_sel_hi:[1,0]
	v_pk_mul_f32 v[2:3], v[2:3], v[36:37] op_sel_hi:[1,0]
	v_fmac_f32_e32 v16, v0, v0
	v_fmac_f32_e32 v16, v1, v1
	v_fmac_f32_e32 v16, v2, v2
	v_pk_mul_f32 v[4:5], v[4:5], v[36:37] op_sel_hi:[1,0]
	v_fmac_f32_e32 v16, v3, v3
	v_fmac_f32_e32 v16, v4, v4
	v_pk_mul_f32 v[6:7], v[6:7], v[36:37] op_sel_hi:[1,0]
	v_fmac_f32_e32 v16, v5, v5
	v_fmac_f32_e32 v16, v6, v6
	v_pk_mul_f32 v[8:9], v[8:9], v[36:37] op_sel_hi:[1,0]
	v_fmac_f32_e32 v16, v7, v7
	v_fmac_f32_e32 v16, v8, v8
	v_pk_mul_f32 v[10:11], v[10:11], v[36:37] op_sel_hi:[1,0]
	v_fmac_f32_e32 v16, v9, v9
	v_fmac_f32_e32 v16, v10, v10
	v_pk_mul_f32 v[12:13], v[12:13], v[36:37] op_sel_hi:[1,0]
	v_fmac_f32_e32 v16, v11, v11
	v_fmac_f32_e32 v16, v12, v12
	v_pk_mul_f32 v[14:15], v[14:15], v[36:37] op_sel_hi:[1,0]
	v_fmac_f32_e32 v16, v13, v13
	v_fmac_f32_e32 v16, v14, v14
	v_fmac_f32_e32 v16, v15, v15
	ds_bpermute_b32 v17, v189, v16
	v_cmp_gt_u32_e32 vcc, 32, v232
	s_and_saveexec_b64 s[0:1], vcc
	s_cbranch_execz .LBB0_284
	s_lshl_b32 s4, s10, 2
	v_lshlrev_b32_e32 v18, 2, v164
	s_add_i32 s4, s4, s20
	v_lshlrev_b32_e32 v19, 2, v252
	v_add3_u32 v18, s4, v18, v19
	s_waitcnt lgkmcnt(0)
	v_add_f32_e32 v16, v16, v17
	ds_write_b32 v18, v16
